# shift4
# speedup vs baseline: 1.0085x; 1.0085x over previous
; __device__ __forceinline__ unsigned xb_ld(unsigned* p)              { return __hip_atomic_load(p, __ATOMIC_RELAXED, __HIP_MEMORY_SCOPE_AGENT); }
; __device__ __forceinline__ unsigned xb_add(unsigned* p, unsigned v) { return __hip_atomic_fetch_add(p, v, __ATOMIC_RELAXED, __HIP_MEMORY_SCOPE_AGENT); }
; __device__ __forceinline__ unsigned xb_xcc_id() { return (unsigned)__builtin_amdgcn_s_getreg((3 << 11) | 20) & 0xFu; }
; #define XB_SPIN(cond, bar) do { unsigned _sp = 0; while (cond) { __builtin_amdgcn_s_sleep(1); \
;     if ((++_sp & 255u) == 0u) { if (xb_ld(&(bar)[XB_TMO])) break; if (_sp > XB_SPIN_CAP) { atomicAdd(&(bar)[XB_TMO], 1u); break; } } } } while (0)
;   volatile unsigned* sh = reinterpret_cast<volatile unsigned*>(g_shm);
;   if (otid(wv) == 0) {
;     const unsigned x = xb_xcc_id();
;     xb_add(&bar[XB_XCNT(x)], 1u);
;     __threadfence();
;     const unsigned G = gridDim.x;
;     const unsigned old = xb_add(&bar[XB_CNT], 1u), gen = old / G;
;     if (old + 1u == (gen + 1u) * G) xb_add(&bar[XB_GEN], 1u); else XB_SPIN(xb_ld(&bar[XB_GEN]) == gen, bar);
; __global__ void __launch_bounds__(NTHREADS, 2) mega(Params p) {
;   cg::grid_group grid = cg::this_grid();
;   const int wv = __builtin_amdgcn_readfirstlane((int)threadIdx.x >> 6);
_Z4mega6Params:
	s_nop 0
	s_load_dword s30, s[0:1], 0x100
	v_and_b32_e32 v1, 0x3ff, v0
	s_add_u32 s28, s0, 0x100
	v_readfirstlane_b32 s93, v1
	s_mov_b32 s6, 31
	s_addc_u32 s29, s1, 0
	s_and_b32 s33, s93, 0xffffffc0
	v_mbcnt_lo_u32_b32 v2, -1, 0
	v_mbcnt_hi_u32_b32 v2, -1, v2
	s_nop 0
	v_or_b32_e32 v2, s33, v2
	v_cmp_eq_u32_e32 vcc, 0, v2
	s_and_saveexec_b64 s[4:5], vcc
	s_cbranch_execz .LBB0_20
	s_ashr_i32 s7, s6, 31
	s_lshl_b64 s[6:7], s[6:7], 3
	s_add_u32 s6, s0, s6
	s_addc_u32 s7, s1, s7
	s_load_dwordx2 s[6:7], s[6:7], 0x0
	s_getreg_b32 s3, hwreg(HW_REG_XCC_ID, 0, 4)
	s_mov_b64 s[10:11], exec
	v_mbcnt_lo_u32_b32 v2, s10, 0
	v_mbcnt_hi_u32_b32 v2, s11, v2
	s_waitcnt lgkmcnt(0)
	s_add_u32 s12, s6, 0x310e8000
	s_addc_u32 s13, s7, 0
	s_and_b32 s3, s3, 15
	s_lshl_b32 s8, s3, 8
	s_add_u32 s8, s12, s8
	s_addc_u32 s9, s13, 0
	v_cmp_eq_u32_e32 vcc, 0, v2
	s_and_saveexec_b64 s[14:15], vcc
	s_cbranch_execz .LBB0_3
	s_bcnt1_i32_b64 s10, s[10:11]
	v_mov_b32_e32 v2, 0
	v_mov_b32_e32 v3, s10
	global_atomic_add v2, v3, s[8:9] offset:1024
